# fused P6: the last BODY's 14 successor-tile staging DMAs (+2 behind its last barrier) fetch the wave's residual fragments into the ring; the epilogue reads them from LDS instead of 16 global loads
# speedup vs baseline: 1.0085x; 1.0085x over previous
;     __device__ __forceinline__ void operator()(f32x4 (&acc)[2][2][4][2], const Unit& u, int wr, int wc, int fr, int fq) const {
;     ...
;             for (int ai = 0; ai < 2; ++ai)
; #pragma unroll
;                 for (int m = 0; m < 4; ++m) { const size_t off = (size_t)(row0 + ai * HALF + m * 16) * ldc + col0;
; #pragma unroll
;                     for (int bj = 0; bj < 2; ++bj) bv[ai][m][bj] = __builtin_nontemporal_load((const u32x4*)(hb + off + bj * HALF)); }
mk_p6_last:
	s_lshl_b32 s98, s75, 8
	s_add_i32 s98, s98, s48
	s_lshl_b32 s98, s98, 12
	s_lshl_b32 s99, s74, 8
	s_or_b32 s99, s99, s50
	s_lshl_b32 s99, s99, 1
	s_add_u32 s98, s98, s99
	s_add_u32 s98, s30, s98
	s_addc_u32 s99, s31, 0
	s_add_u32 s100, s98, 0x100
	s_addc_u32 s101, s99, 0
	v_mbcnt_lo_u32_b32 v249, -1, 0
	v_mbcnt_hi_u32_b32 v249, -1, v249
	v_and_b32_e32 v248, 15, v249
	v_lshrrev_b32_e32 v249, 4, v249
	v_lshlrev_b32_e32 v249, 4, v249
	v_lshl_or_b32 v249, v248, 12, v249
	s_add_u32 s42, s20, 0x100
	s_addc_u32 s43, s21, 0
	s_cmpk_eq_i32 s89, 0x7c
	s_cselect_b32 s28, s86, s42
	s_cselect_b32 s29, s81, s43
	s_cselect_b32 s23, s37, s88
	s_cselect_b32 s22, s87, vcc_lo
	s_add_u32 s26, s28, 0x80
	s_addc_u32 s27, s29, 0
	s_add_u32 s66, s22, 0x80
	s_addc_u32 s67, s23, 0
	s_add_u32 s90, s20, 0x200080
	s_addc_u32 s91, s21, 0
	s_add_u32 s52, s28, 0x200000
	s_addc_u32 s53, s29, 0
	s_add_u32 s56, s22, 0x200000
	s_addc_u32 s57, s23, 0
	s_add_u32 s20, s22, 0x200080
	s_addc_u32 s21, s23, 0
	s_add_i32 s92, 0, 0x10000
	s_add_i32 s93, 0, 0x14000
	v_add_u32_e32 v140, s92, v203
	v_add_u32_e32 v156, s93, v203
	ds_read_b128 v[128:131], v140
	ds_read_b128 v[132:135], v140 offset:1024
	ds_read_b128 v[136:139], v140 offset:2048
	ds_read_b128 v[140:143], v140 offset:3072
	ds_read_b128 v[144:147], v156
	ds_read_b128 v[148:151], v156 offset:1024
	ds_read_b128 v[152:155], v156 offset:2048
	ds_read_b128 v[156:159], v156 offset:3072
	s_add_i32 m0, s73, 0xc000
	ds_read_b128 v[160:163], v205
	ds_read_b128 v[164:167], v205 offset:1024
	ds_read_b128 v[168:171], v205 offset:2048
	ds_read_b128 v[172:175], v205 offset:3072
	ds_read_b128 v[176:179], v205 offset:4096
	ds_read_b128 v[180:183], v205 offset:5120
	ds_read_b128 v[184:187], v205 offset:6144
	ds_read_b128 v[188:191], v205 offset:7168
	global_load_lds_dwordx4 v202, s[90:91]
	s_add_i32 m0, s73, 0xe000
	s_nop 0
	global_load_lds_dwordx4 v204, s[90:91]
	s_waitcnt vmcnt(8)
	s_waitcnt lgkmcnt(0)
	s_barrier
	s_setprio 1
	s_waitcnt lgkmcnt(0)
	v_mfma_f32_16x16x32_bf16 v[124:127], v[128:131], v[160:163], v[124:127]
	v_mfma_f32_16x16x32_bf16 v[120:123], v[136:139], v[160:163], v[120:123]
	v_mfma_f32_16x16x32_bf16 v[108:111], v[128:131], v[168:171], v[108:111]
	v_mfma_f32_16x16x32_bf16 v[104:107], v[136:139], v[168:171], v[104:107]
	v_mfma_f32_16x16x32_bf16 v[92:95], v[128:131], v[176:179], v[92:95]
	v_mfma_f32_16x16x32_bf16 v[88:91], v[136:139], v[176:179], v[88:91]
	v_mfma_f32_16x16x32_bf16 v[76:79], v[128:131], v[184:187], v[76:79]
	v_mfma_f32_16x16x32_bf16 v[72:75], v[136:139], v[184:187], v[72:75]
	v_mfma_f32_16x16x32_bf16 v[124:127], v[132:135], v[164:167], v[124:127]
	v_mfma_f32_16x16x32_bf16 v[120:123], v[140:143], v[164:167], v[120:123]
	v_mfma_f32_16x16x32_bf16 v[108:111], v[132:135], v[172:175], v[108:111]
	v_mfma_f32_16x16x32_bf16 v[104:107], v[140:143], v[172:175], v[104:107]
	v_mfma_f32_16x16x32_bf16 v[92:95], v[132:135], v[180:183], v[92:95]
	v_mfma_f32_16x16x32_bf16 v[88:91], v[140:143], v[180:183], v[88:91]
	v_mfma_f32_16x16x32_bf16 v[76:79], v[132:135], v[188:191], v[76:79]
	v_mfma_f32_16x16x32_bf16 v[72:75], v[140:143], v[188:191], v[72:75]
	s_setprio 0
	s_setprio 1
	v_mfma_f32_16x16x32_bf16 v[116:119], v[144:147], v[160:163], v[116:119]
	v_mfma_f32_16x16x32_bf16 v[112:115], v[152:155], v[160:163], v[112:115]
	v_mfma_f32_16x16x32_bf16 v[100:103], v[144:147], v[168:171], v[100:103]
	v_mfma_f32_16x16x32_bf16 v[96:99], v[152:155], v[168:171], v[96:99]
	v_mfma_f32_16x16x32_bf16 v[84:87], v[144:147], v[176:179], v[84:87]
	v_mfma_f32_16x16x32_bf16 v[80:83], v[152:155], v[176:179], v[80:83]
	v_mfma_f32_16x16x32_bf16 v[68:71], v[144:147], v[184:187], v[68:71]
	v_mfma_f32_16x16x32_bf16 v[64:67], v[152:155], v[184:187], v[64:67]
	v_mfma_f32_16x16x32_bf16 v[116:119], v[148:151], v[164:167], v[116:119]
	v_mfma_f32_16x16x32_bf16 v[112:115], v[156:159], v[164:167], v[112:115]
	v_mfma_f32_16x16x32_bf16 v[100:103], v[148:151], v[172:175], v[100:103]
	v_mfma_f32_16x16x32_bf16 v[96:99], v[156:159], v[172:175], v[96:99]
	v_mfma_f32_16x16x32_bf16 v[84:87], v[148:151], v[180:183], v[84:87]
	v_mfma_f32_16x16x32_bf16 v[80:83], v[156:159], v[180:183], v[80:83]
	v_mfma_f32_16x16x32_bf16 v[68:71], v[148:151], v[188:191], v[68:71]
	v_mfma_f32_16x16x32_bf16 v[64:67], v[156:159], v[188:191], v[64:67]
	s_setprio 0
	s_barrier
	s_add_i32 s90, s92, s33
	s_mov_b32 m0, s90
	ds_read_b128 v[160:163], v205 offset:16384
	ds_read_b128 v[164:167], v205 offset:17408
	ds_read_b128 v[168:171], v205 offset:18432
	ds_read_b128 v[172:175], v205 offset:19456
	ds_read_b128 v[176:179], v205 offset:20480
	ds_read_b128 v[180:183], v205 offset:21504
	ds_read_b128 v[184:187], v205 offset:22528
	ds_read_b128 v[188:191], v205 offset:23552
	global_load_lds_dwordx4 v249, s[98:99]
	s_add_i32 m0, s90, 0x2000
	s_nop 0
	global_load_lds_dwordx4 v249, s[100:101]
	s_add_i32 s22, s93, s33
	s_mov_b32 m0, s22
	s_nop 0
	s_add_u32 s98, s98, 0x10000
	s_addc_u32 s99, s99, 0
	s_add_u32 s100, s100, 0x10000
	s_addc_u32 s101, s101, 0
	global_load_lds_dwordx4 v249, s[98:99]
	s_add_i32 m0, s22, 0x2000
	s_nop 0
	global_load_lds_dwordx4 v249, s[100:101]
	s_mov_b32 m0, s73
	s_nop 0
	s_add_u32 s98, s98, 0x10000
	s_addc_u32 s99, s99, 0
	s_add_u32 s100, s100, 0x10000
	s_addc_u32 s101, s101, 0
	global_load_lds_dwordx4 v249, s[98:99]
	s_mov_b32 m0, s34
	s_nop 0
	global_load_lds_dwordx4 v249, s[100:101]
	s_waitcnt vmcnt(8)
	s_waitcnt lgkmcnt(0)
	s_barrier
	s_setprio 1
	s_waitcnt lgkmcnt(0)
	v_mfma_f32_16x16x32_bf16 v[60:63], v[128:131], v[160:163], v[60:63]
	v_mfma_f32_16x16x32_bf16 v[56:59], v[136:139], v[160:163], v[56:59]
	v_mfma_f32_16x16x32_bf16 v[44:47], v[128:131], v[168:171], v[44:47]
	v_mfma_f32_16x16x32_bf16 v[40:43], v[136:139], v[168:171], v[40:43]
	v_mfma_f32_16x16x32_bf16 v[28:31], v[128:131], v[176:179], v[28:31]
	v_mfma_f32_16x16x32_bf16 v[24:27], v[136:139], v[176:179], v[24:27]
	v_mfma_f32_16x16x32_bf16 v[12:15], v[128:131], v[184:187], v[12:15]
	v_mfma_f32_16x16x32_bf16 v[8:11], v[136:139], v[184:187], v[8:11]
	v_mfma_f32_16x16x32_bf16 v[60:63], v[132:135], v[164:167], v[60:63]
	v_mfma_f32_16x16x32_bf16 v[56:59], v[140:143], v[164:167], v[56:59]
	v_mfma_f32_16x16x32_bf16 v[44:47], v[132:135], v[172:175], v[44:47]
	v_mfma_f32_16x16x32_bf16 v[40:43], v[140:143], v[172:175], v[40:43]
	v_mfma_f32_16x16x32_bf16 v[28:31], v[132:135], v[180:183], v[28:31]
	v_mfma_f32_16x16x32_bf16 v[24:27], v[140:143], v[180:183], v[24:27]
	v_mfma_f32_16x16x32_bf16 v[12:15], v[132:135], v[188:191], v[12:15]
	v_mfma_f32_16x16x32_bf16 v[8:11], v[140:143], v[188:191], v[8:11]
	s_setprio 0
	s_setprio 1
	v_mfma_f32_16x16x32_bf16 v[52:55], v[144:147], v[160:163], v[52:55]
	v_mfma_f32_16x16x32_bf16 v[48:51], v[152:155], v[160:163], v[48:51]
	v_mfma_f32_16x16x32_bf16 v[36:39], v[144:147], v[168:171], v[36:39]
	v_mfma_f32_16x16x32_bf16 v[32:35], v[152:155], v[168:171], v[32:35]
	v_mfma_f32_16x16x32_bf16 v[20:23], v[144:147], v[176:179], v[20:23]
	v_mfma_f32_16x16x32_bf16 v[16:19], v[152:155], v[176:179], v[16:19]
	v_mfma_f32_16x16x32_bf16 v[4:7], v[144:147], v[184:187], v[4:7]
	v_mfma_f32_16x16x32_bf16 v[0:3], v[152:155], v[184:187], v[0:3]
	v_mfma_f32_16x16x32_bf16 v[52:55], v[148:151], v[164:167], v[52:55]
	v_mfma_f32_16x16x32_bf16 v[48:51], v[156:159], v[164:167], v[48:51]
	v_mfma_f32_16x16x32_bf16 v[36:39], v[148:151], v[172:175], v[36:39]
	v_mfma_f32_16x16x32_bf16 v[32:35], v[156:159], v[172:175], v[32:35]
	v_mfma_f32_16x16x32_bf16 v[20:23], v[148:151], v[180:183], v[20:23]
	v_mfma_f32_16x16x32_bf16 v[16:19], v[156:159], v[180:183], v[16:19]
	v_mfma_f32_16x16x32_bf16 v[4:7], v[148:151], v[188:191], v[4:7]
	v_mfma_f32_16x16x32_bf16 v[0:3], v[156:159], v[188:191], v[0:3]
	s_setprio 0
	s_barrier
	s_add_i32 s22, 0, 0x18000
	s_add_i32 s23, 0, 0x1c000
	v_add_u32_e32 v140, s22, v203
	v_add_u32_e32 v156, s23, v203
	ds_read_b128 v[128:131], v140
	ds_read_b128 v[132:135], v140 offset:1024
	ds_read_b128 v[136:139], v140 offset:2048
	ds_read_b128 v[140:143], v140 offset:3072
	ds_read_b128 v[144:147], v156
	ds_read_b128 v[148:151], v156 offset:1024
	ds_read_b128 v[152:155], v156 offset:2048
	ds_read_b128 v[156:159], v156 offset:3072
	s_mov_b32 m0, s35
	ds_read_b128 v[160:163], v205 offset:32768
	ds_read_b128 v[164:167], v205 offset:33792
	ds_read_b128 v[168:171], v205 offset:34816
	ds_read_b128 v[172:175], v205 offset:35840
	ds_read_b128 v[176:179], v205 offset:36864
	ds_read_b128 v[180:183], v205 offset:37888
	ds_read_b128 v[184:187], v205 offset:38912
	ds_read_b128 v[188:191], v205 offset:39936
	s_add_u32 s98, s98, 0x10000
	s_addc_u32 s99, s99, 0
	s_add_u32 s100, s100, 0x10000
	s_addc_u32 s101, s101, 0
	global_load_lds_dwordx4 v249, s[98:99]
	s_mov_b32 m0, s0
	s_nop 0
	global_load_lds_dwordx4 v249, s[100:101]
	s_waitcnt vmcnt(8)
	s_waitcnt lgkmcnt(0)
	s_barrier
	s_setprio 1
	s_waitcnt lgkmcnt(0)
	v_mfma_f32_16x16x32_bf16 v[124:127], v[128:131], v[160:163], v[124:127]
	v_mfma_f32_16x16x32_bf16 v[120:123], v[136:139], v[160:163], v[120:123]
	v_mfma_f32_16x16x32_bf16 v[108:111], v[128:131], v[168:171], v[108:111]
	v_mfma_f32_16x16x32_bf16 v[104:107], v[136:139], v[168:171], v[104:107]
	v_mfma_f32_16x16x32_bf16 v[92:95], v[128:131], v[176:179], v[92:95]
	v_mfma_f32_16x16x32_bf16 v[88:91], v[136:139], v[176:179], v[88:91]
	v_mfma_f32_16x16x32_bf16 v[76:79], v[128:131], v[184:187], v[76:79]
	v_mfma_f32_16x16x32_bf16 v[72:75], v[136:139], v[184:187], v[72:75]
	v_mfma_f32_16x16x32_bf16 v[124:127], v[132:135], v[164:167], v[124:127]
	v_mfma_f32_16x16x32_bf16 v[120:123], v[140:143], v[164:167], v[120:123]
	v_mfma_f32_16x16x32_bf16 v[108:111], v[132:135], v[172:175], v[108:111]
	v_mfma_f32_16x16x32_bf16 v[104:107], v[140:143], v[172:175], v[104:107]
	v_mfma_f32_16x16x32_bf16 v[92:95], v[132:135], v[180:183], v[92:95]
	v_mfma_f32_16x16x32_bf16 v[88:91], v[140:143], v[180:183], v[88:91]
	v_mfma_f32_16x16x32_bf16 v[76:79], v[132:135], v[188:191], v[76:79]
	v_mfma_f32_16x16x32_bf16 v[72:75], v[140:143], v[188:191], v[72:75]
	s_setprio 0
	s_setprio 1
	v_mfma_f32_16x16x32_bf16 v[116:119], v[144:147], v[160:163], v[116:119]
	v_mfma_f32_16x16x32_bf16 v[112:115], v[152:155], v[160:163], v[112:115]
	v_mfma_f32_16x16x32_bf16 v[100:103], v[144:147], v[168:171], v[100:103]
	v_mfma_f32_16x16x32_bf16 v[96:99], v[152:155], v[168:171], v[96:99]
	v_mfma_f32_16x16x32_bf16 v[84:87], v[144:147], v[176:179], v[84:87]
	v_mfma_f32_16x16x32_bf16 v[80:83], v[152:155], v[176:179], v[80:83]
	v_mfma_f32_16x16x32_bf16 v[68:71], v[144:147], v[184:187], v[68:71]
	v_mfma_f32_16x16x32_bf16 v[64:67], v[152:155], v[184:187], v[64:67]
	v_mfma_f32_16x16x32_bf16 v[116:119], v[148:151], v[164:167], v[116:119]
	v_mfma_f32_16x16x32_bf16 v[112:115], v[156:159], v[164:167], v[112:115]
	v_mfma_f32_16x16x32_bf16 v[100:103], v[148:151], v[172:175], v[100:103]
	v_mfma_f32_16x16x32_bf16 v[96:99], v[156:159], v[172:175], v[96:99]
	v_mfma_f32_16x16x32_bf16 v[84:87], v[148:151], v[180:183], v[84:87]
	v_mfma_f32_16x16x32_bf16 v[80:83], v[156:159], v[180:183], v[80:83]
	v_mfma_f32_16x16x32_bf16 v[68:71], v[148:151], v[188:191], v[68:71]
	v_mfma_f32_16x16x32_bf16 v[64:67], v[156:159], v[188:191], v[64:67]
	s_setprio 0
	s_barrier
; #define PG8_MMA(ai, bj, At, Bt) do { __builtin_amdgcn_s_setprio(1); _Pragma("unroll") for (int m = 0; m < 4; ++m) _Pragma("unroll") for (int n = 0; n < 2; ++n) _Pragma("unroll") for (int k = 0; k < 2; ++k) \
;         acc[ai][bj][m][n] = __builtin_amdgcn_mfma_f32_16x16x32_bf16(Bt[n][k], At[m][k], acc[ai][bj][m][n], 0, 0, 0); __builtin_amdgcn_s_setprio(0); } while (0)
;     ...
;         { const int tmid = (TSW > 0 && TSW < nt) ? TSW : nt;
;           _Pragma("unroll 1") for (int t = 0; t < tmid; t += 2) { PG8_BODY(PG8_MMA) }
	s_add_i32 s22, s22, s33
	s_mov_b32 m0, s22
	ds_read_b128 v[160:163], v205 offset:49152
	ds_read_b128 v[164:167], v205 offset:50176
	ds_read_b128 v[168:171], v205 offset:51200
	ds_read_b128 v[172:175], v205 offset:52224
	ds_read_b128 v[176:179], v205 offset:53248
	ds_read_b128 v[180:183], v205 offset:54272
	ds_read_b128 v[184:187], v205 offset:55296
	ds_read_b128 v[188:191], v205 offset:56320
	s_add_u32 s98, s98, 0x50000
	s_addc_u32 s99, s99, 0
	s_add_u32 s100, s100, 0x50000
	s_addc_u32 s101, s101, 0
	global_load_lds_dwordx4 v249, s[98:99]
	s_add_i32 m0, s22, 0x2000
	s_add_i32 s22, s23, s33
	global_load_lds_dwordx4 v249, s[100:101]
	s_mov_b32 m0, s22
	s_nop 0
	s_add_u32 s98, s98, 0x10000
	s_addc_u32 s99, s99, 0
	s_add_u32 s100, s100, 0x10000
	s_addc_u32 s101, s101, 0
	global_load_lds_dwordx4 v249, s[98:99]
	s_add_i32 m0, s22, 0x2000
	s_nop 0
	global_load_lds_dwordx4 v249, s[100:101]
	s_mov_b32 m0, s1
	s_nop 0
	s_add_u32 s98, s98, 0x10000
	s_addc_u32 s99, s99, 0
	s_add_u32 s100, s100, 0x10000
	s_addc_u32 s101, s101, 0
	global_load_lds_dwordx4 v249, s[98:99]
	s_mov_b32 m0, s54
	s_nop 0
	global_load_lds_dwordx4 v249, s[100:101]
	s_waitcnt vmcnt(8)
	s_waitcnt lgkmcnt(0)
	s_barrier
	s_setprio 1
	s_waitcnt lgkmcnt(0)
	v_mfma_f32_16x16x32_bf16 v[60:63], v[128:131], v[160:163], v[60:63]
	v_mfma_f32_16x16x32_bf16 v[56:59], v[136:139], v[160:163], v[56:59]
	v_mfma_f32_16x16x32_bf16 v[44:47], v[128:131], v[168:171], v[44:47]
	v_mfma_f32_16x16x32_bf16 v[40:43], v[136:139], v[168:171], v[40:43]
	v_mfma_f32_16x16x32_bf16 v[28:31], v[128:131], v[176:179], v[28:31]
	v_mfma_f32_16x16x32_bf16 v[24:27], v[136:139], v[176:179], v[24:27]
	v_mfma_f32_16x16x32_bf16 v[12:15], v[128:131], v[184:187], v[12:15]
	v_mfma_f32_16x16x32_bf16 v[8:11], v[136:139], v[184:187], v[8:11]
	v_mfma_f32_16x16x32_bf16 v[60:63], v[132:135], v[164:167], v[60:63]
	v_mfma_f32_16x16x32_bf16 v[56:59], v[140:143], v[164:167], v[56:59]
	v_mfma_f32_16x16x32_bf16 v[44:47], v[132:135], v[172:175], v[44:47]
	v_mfma_f32_16x16x32_bf16 v[40:43], v[140:143], v[172:175], v[40:43]
	v_mfma_f32_16x16x32_bf16 v[28:31], v[132:135], v[180:183], v[28:31]
	v_mfma_f32_16x16x32_bf16 v[24:27], v[140:143], v[180:183], v[24:27]
	v_mfma_f32_16x16x32_bf16 v[12:15], v[132:135], v[188:191], v[12:15]
	v_mfma_f32_16x16x32_bf16 v[8:11], v[140:143], v[188:191], v[8:11]
	s_setprio 0
	s_setprio 1
	v_mfma_f32_16x16x32_bf16 v[52:55], v[144:147], v[160:163], v[52:55]
	v_mfma_f32_16x16x32_bf16 v[48:51], v[152:155], v[160:163], v[48:51]
	v_mfma_f32_16x16x32_bf16 v[36:39], v[144:147], v[168:171], v[36:39]
	v_mfma_f32_16x16x32_bf16 v[32:35], v[152:155], v[168:171], v[32:35]
	v_mfma_f32_16x16x32_bf16 v[20:23], v[144:147], v[176:179], v[20:23]
	v_mfma_f32_16x16x32_bf16 v[16:19], v[152:155], v[176:179], v[16:19]
	v_mfma_f32_16x16x32_bf16 v[4:7], v[144:147], v[184:187], v[4:7]
	v_mfma_f32_16x16x32_bf16 v[0:3], v[152:155], v[184:187], v[0:3]
	v_mfma_f32_16x16x32_bf16 v[52:55], v[148:151], v[164:167], v[52:55]
	v_mfma_f32_16x16x32_bf16 v[48:51], v[156:159], v[164:167], v[48:51]
	v_mfma_f32_16x16x32_bf16 v[36:39], v[148:151], v[172:175], v[36:39]
	v_mfma_f32_16x16x32_bf16 v[32:35], v[156:159], v[172:175], v[32:35]
	v_mfma_f32_16x16x32_bf16 v[20:23], v[148:151], v[180:183], v[20:23]
	v_mfma_f32_16x16x32_bf16 v[16:19], v[156:159], v[180:183], v[16:19]
	v_mfma_f32_16x16x32_bf16 v[4:7], v[148:151], v[188:191], v[4:7]
	v_mfma_f32_16x16x32_bf16 v[0:3], v[156:159], v[188:191], v[0:3]
	s_setprio 0
	s_barrier
	s_add_u32 s98, s98, 0x10000
	s_addc_u32 s99, s99, 0
	s_add_u32 s100, s100, 0x10000
	s_addc_u32 s101, s101, 0
	s_add_i32 m0, s73, 0xc000
	s_nop 0
	global_load_lds_dwordx4 v249, s[98:99]
	s_add_i32 m0, s73, 0xe000
	s_nop 0
	global_load_lds_dwordx4 v249, s[100:101]
	s_add_i32 s89, s89, 2
	s_add_u32 vcc_lo, vcc_lo, 0x100
	s_addc_u32 s88, s88, 0
	s_mov_b64 s[20:21], s[42:43]

; __device__ __forceinline__ unsigned lane_id_fresh() { unsigned m = ~0u; asm volatile("" : "+s"(m)); return __builtin_amdgcn_mbcnt_hi(m, __builtin_amdgcn_mbcnt_lo(m, 0u)); }
;     __device__ __forceinline__ void operator()(f32x4 (&acc)[2][2][4][2], const Unit& u, int wr, int wc, int fr, int fq) const {
;         int l_ = (int)lane_id_fresh(); asm volatile("" : "+v"(l_)); fr = l_ & 15; fq = l_ >> 4;
;         const int row0 = u.pm * BM + wr * 64 + fr, col0 = u.pn * BM + wc * 32 + 8 * fq;
;         {
;             u32x4 bv[2][4][2];
; #pragma unroll
;             for (int ai = 0; ai < 2; ++ai)
; #pragma unroll
;                 for (int m = 0; m < 4; ++m) { const size_t off = (size_t)(row0 + ai * HALF + m * 16) * ldc + col0;
; #pragma unroll
;                     for (int bj = 0; bj < 2; ++bj) bv[ai][m][bj] = __builtin_nontemporal_load((const u32x4*)(hb + off + bj * HALF)); }
; #pragma unroll
;             for (int ai = 0; ai < 2; ++ai)
; #pragma unroll
;                 for (int m = 0; m < 4; ++m) { const int r = row0 + ai * HALF + m * 16; float s = 0.f;
; #pragma unroll
;                     for (int bj = 0; bj < 2; ++bj) { const u32x4 b = bv[ai][m][bj];
;                         f32x4 o0 = acc[ai][bj][m][0], o1 = acc[ai][bj][m][1];
;                         o0[0] += __builtin_bit_cast(float, b.x << 16); o0[1] += __builtin_bit_cast(float, b.x & 0xffff0000u);
;                         o0[2] += __builtin_bit_cast(float, b.y << 16); o0[3] += __builtin_bit_cast(float, b.y & 0xffff0000u);
;                         o1[0] += __builtin_bit_cast(float, b.z << 16); o1[1] += __builtin_bit_cast(float, b.z & 0xffff0000u);
;                         o1[2] += __builtin_bit_cast(float, b.w << 16); o1[3] += __builtin_bit_cast(float, b.w & 0xffff0000u);
;                         s += ((o0[0] * o0[0] + o0[1] * o0[1]) + (o0[2] * o0[2] + o0[3] * o0[3])) + ((o1[0] * o1[0] + o1[1] * o1[1]) + (o1[2] * o1[2] + o1[3] * o1[3]));
;                         acc[ai][bj][m][0] = o0; acc[ai][bj][m][1] = o1; }
;                     s += __shfl_xor(s, 16); s += __shfl_xor(s, 32);
;                     if (fq == 0) (void)__hip_atomic_fetch_add(sx + r, (1ull << 40) | (unsigned long long)(s * 16384.0f + 0.5f), __ATOMIC_RELAXED, __HIP_MEMORY_SCOPE_AGENT); }
.LBB0_886:
	s_mov_b32 s20, s70
	s_lshl_b32 s21, s74, 8
	v_mbcnt_lo_u32_b32 v128, s20, 0
	v_mbcnt_hi_u32_b32 v231, s20, v128
	s_lshl_b32 s20, s75, 8
	v_ashrrev_i32_e32 v128, 1, v231
	s_add_i32 s20, s20, s48
	s_or_b32 s21, s21, s50
	v_and_b32_e32 v128, -8, v128
	v_and_or_b32 v210, v231, 15, s20
	v_add_u32_e32 v208, s21, v128
	v_ashrrev_i32_e32 v209, 31, v208
	v_ashrrev_i32_e32 v211, 31, v210
	v_lshl_add_u64 v[136:137], v[208:209], 1, s[30:31]
	v_lshlrev_b64 v[128:129], 12, v[210:211]
	v_lshl_add_u64 v[128:129], v[136:137], 0, v[128:129]
	v_mbcnt_lo_u32_b32 v248, -1, 0
	v_mbcnt_hi_u32_b32 v248, -1, v248
	v_lshl_add_u32 v248, v248, 4, s33
	v_add_u32_e32 v250, 0x10000, v248
	s_waitcnt vmcnt(0)
	ds_read_b128 v[188:191], v250 offset:0
	ds_read_b128 v[184:187], v250 offset:8192
	v_or_b32_e32 v212, 16, v210
	v_ashrrev_i32_e32 v213, 31, v212
	v_lshlrev_b64 v[128:129], 12, v[212:213]
	v_or_b32_e32 v214, 32, v210
	v_lshl_add_u64 v[128:129], v[136:137], 0, v[128:129]
	v_ashrrev_i32_e32 v215, 31, v214
	ds_read_b128 v[180:183], v250 offset:16384
	ds_read_b128 v[176:179], v250 offset:24576
	v_lshlrev_b64 v[128:129], 12, v[214:215]
	v_or_b32_e32 v216, 48, v210
	v_lshl_add_u64 v[128:129], v[136:137], 0, v[128:129]
	v_ashrrev_i32_e32 v217, 31, v216
	ds_read_b128 v[172:175], v248 offset:0
	ds_read_b128 v[168:171], v248 offset:8192
	v_lshlrev_b64 v[128:129], 12, v[216:217]
	v_add_u32_e32 v218, 0x80, v210
	v_lshl_add_u64 v[128:129], v[136:137], 0, v[128:129]
	v_ashrrev_i32_e32 v219, 31, v218
	ds_read_b128 v[164:167], v248 offset:16384
	ds_read_b128 v[160:163], v248 offset:24576
	v_lshlrev_b64 v[128:129], 12, v[218:219]
	v_add_u32_e32 v220, 0x90, v210
	v_lshl_add_u64 v[128:129], v[136:137], 0, v[128:129]
	v_ashrrev_i32_e32 v221, 31, v220
	ds_read_b128 v[156:159], v250 offset:32768
	ds_read_b128 v[152:155], v250 offset:40960
	v_lshlrev_b64 v[128:129], 12, v[220:221]
	v_add_u32_e32 v222, 0xa0, v210
	v_add_u32_e32 v224, 0xb0, v210
	v_lshl_add_u64 v[128:129], v[136:137], 0, v[128:129]
	v_ashrrev_i32_e32 v223, 31, v222
	v_ashrrev_i32_e32 v225, 31, v224
	ds_read_b128 v[148:151], v250 offset:49152
	ds_read_b128 v[140:143], v250 offset:57344
	v_lshlrev_b64 v[128:129], 12, v[222:223]
	v_lshlrev_b64 v[138:139], 12, v[224:225]
	v_lshl_add_u64 v[128:129], v[136:137], 0, v[128:129]
	v_lshl_add_u64 v[136:137], v[136:137], 0, v[138:139]
	ds_read_b128 v[132:135], v248 offset:32768
	s_nop 0
	ds_read_b128 v[128:131], v248 offset:40960
	s_nop 0
	ds_read_b128 v[144:147], v248 offset:49152
	s_nop 0
	ds_read_b128 v[136:139], v248 offset:57344
	v_and_b32_e32 v230, 64, v229
	v_xor_b32_e32 v207, 16, v229
	v_add_u32_e32 v230, 64, v230
	v_cmp_lt_i32_e32 vcc, v207, v230
	v_xor_b32_e32 v232, 32, v229
	s_waitcnt lgkmcnt(0)
	v_and_b32_e32 v233, 0xffff0000, v188
	v_cndmask_b32_e32 v207, v229, v207, vcc
	v_cmp_lt_i32_e32 vcc, v232, v230
	v_lshlrev_b32_e32 v236, 16, v184
	v_and_b32_e32 v237, 0xffff0000, v184
	v_cndmask_b32_e32 v230, v229, v232, vcc
	v_lshlrev_b32_e32 v232, 16, v188
	v_lshlrev_b32_e32 v188, 16, v189
	v_and_b32_e32 v189, 0xffff0000, v189
	v_lshlrev_b32_e32 v184, 16, v185
	v_and_b32_e32 v185, 0xffff0000, v185
	v_pk_add_f32 v[126:127], v[126:127], v[188:189]
	v_lshlrev_b32_e32 v188, 16, v190
	v_and_b32_e32 v189, 0xffff0000, v190
	v_pk_add_f32 v[118:119], v[118:119], v[184:185]
	v_lshlrev_b32_e32 v184, 16, v186
	v_and_b32_e32 v185, 0xffff0000, v186
	v_pk_add_f32 v[120:121], v[120:121], v[188:189]
	v_lshlrev_b32_e32 v188, 16, v191
	v_and_b32_e32 v189, 0xffff0000, v191
	v_pk_add_f32 v[116:117], v[116:117], v[236:237]
	v_pk_add_f32 v[112:113], v[112:113], v[184:185]
	v_lshlrev_b32_e32 v184, 16, v187
	v_and_b32_e32 v185, 0xffff0000, v187
	v_pk_add_f32 v[122:123], v[122:123], v[188:189]
	v_pk_add_f32 v[114:115], v[114:115], v[184:185]
	v_pk_mul_f32 v[184:185], v[116:117], v[116:117]
	v_pk_mul_f32 v[186:187], v[118:119], v[118:119]
	v_pk_add_f32 v[124:125], v[124:125], v[232:233]
	v_pk_mul_f32 v[232:233], v[120:121], v[120:121]
	v_pk_mul_f32 v[234:235], v[122:123], v[122:123]
	v_add_f32_e32 v186, v186, v187
	v_add_f32_e32 v184, v184, v185
	v_pk_mul_f32 v[188:189], v[124:125], v[124:125]
	v_pk_mul_f32 v[190:191], v[126:127], v[126:127]
	v_pk_mul_f32 v[236:237], v[112:113], v[112:113]
	v_pk_mul_f32 v[238:239], v[114:115], v[114:115]
	v_add_f32_e32 v184, v184, v186
	v_add_f32_e32 v185, v234, v235
	v_add_f32_e32 v186, v232, v233
	v_cmp_gt_u32_e32 vcc, 16, v231
	v_add_f32_e32 v231, v238, v239
	v_add_f32_e32 v236, v236, v237
	v_add_f32_e32 v185, v186, v185
	v_add_f32_e32 v186, v190, v191
	v_add_f32_e32 v187, v188, v189
	v_add_f32_e32 v231, v236, v231
	v_add_f32_e32 v186, v187, v186
	v_add_f32_e32 v184, v184, v231
	v_add_f32_e32 v185, v186, v185
	v_lshlrev_b32_e32 v207, 2, v207
	v_add_f32_e32 v184, v185, v184
	ds_bpermute_b32 v185, v207, v184
	v_lshlrev_b32_e32 v230, 2, v230
	s_waitcnt lgkmcnt(0)
	v_add_f32_e32 v186, v184, v185
	ds_bpermute_b32 v187, v230, v186
	v_lshl_add_u64 v[184:185], v[210:211], 3, s[46:47]
	s_and_saveexec_b64 s[22:23], vcc
	s_cbranch_execz .LBB0_888
	s_waitcnt lgkmcnt(0)
	v_add_f32_e32 v186, v186, v187
	v_fma_f32 v186, v186, s72, 0.5
	v_trunc_f32_e32 v186, v186
	v_mul_f32_e32 v187, 0x2f800000, v186
	v_floor_f32_e32 v187, v187
	v_fmac_f32_e32 v186, 0xcf800000, v187
	v_cvt_u32_f32_e32 v187, v187
	v_cvt_u32_f32_e32 v186, v186
	v_or_b32_e32 v187, 0x100, v187
	global_atomic_add_x2 v[184:185], v[186:187], off
